# P1 row loop: rows m+2..m+4 prefetched by LDS-DMA into a per-wave LDS ring (3 slots), read back with ds_read_b128 behind counted vmcnt; the compiler loop waited for row m+2 inside iteration m
# speedup vs baseline: 1.0142x; 1.0142x over previous
; __device__ __forceinline__ void phase1(const Args& a, LAS unsigned char* L) {
;     ...
;     int m_lo = gw * RPW, m_hi = m_lo + RPW; if (m_hi > MT) m_hi = MT;
;     int curb = -1; f32x4 gsv[4], shv[4];
; #pragma unroll
;     for (int j = 0; j < 4; ++j) { gsv[j] = (f32x4){0.f, 0.f, 0.f, 0.f}; shv[j] = gsv[j]; }
;     f32x4 nxv[4], nxw[4];
; #pragma unroll
;     for (int j = 0; j < 4; ++j) { nxv[j] = (f32x4){0.f, 0.f, 0.f, 0.f}; nxw[j] = nxv[j]; }
;     if (m_lo < m_hi) { const float* xr = (m_lo < MP ? a.in[0] + (size_t)m_lo * DM : a.in[1] + (size_t)(m_lo - MP) * DM);
; #pragma unroll
;         for (int j = 0; j < 4; ++j) nxv[j] = *(const f32x4*)(xr + 4 * lane + 256 * j); }
;     if (m_lo + 1 < m_hi) { const int m1 = m_lo + 1; const float* xr = (m1 < MP ? a.in[0] + (size_t)m1 * DM : a.in[1] + (size_t)(m1 - MP) * DM);
; #pragma unroll
;         for (int j = 0; j < 4; ++j) nxw[j] = *(const f32x4*)(xr + 4 * lane + 256 * j); }
.LBB0_115:
	v_mbcnt_hi_u32_b32 v3, -1, v181
	v_and_b32_e32 v36, 64, v3
	v_add_u32_e32 v36, 64, v36
	v_xor_b32_e32 v37, 1, v3
	v_cmp_lt_i32_e32 vcc, v37, v36
	s_add_u32 s58, s28, 0x1e100000
	s_addc_u32 s59, s29, 0
	v_cndmask_b32_e32 v37, v3, v37, vcc
	v_lshlrev_b32_e32 v165, 2, v37
	v_xor_b32_e32 v37, 2, v3
	v_cmp_lt_i32_e32 vcc, v37, v36
	v_lshlrev_b32_e32 v164, 2, v2
	s_add_u32 s0, s54, 0x1000
	v_cndmask_b32_e32 v37, v3, v37, vcc
	v_lshlrev_b32_e32 v182, 2, v37
	v_xor_b32_e32 v37, 4, v3
	v_cmp_lt_i32_e32 vcc, v37, v36
	v_mov_b32_e32 v1, 0
	s_addc_u32 s1, s55, 0
	v_cndmask_b32_e32 v37, v3, v37, vcc
	v_lshlrev_b32_e32 v183, 2, v37
	v_xor_b32_e32 v37, 8, v3
	v_cmp_lt_i32_e32 vcc, v37, v36
	v_mov_b32_e32 v39, v1
	v_mov_b32_e32 v41, v1
	v_cndmask_b32_e32 v37, v3, v37, vcc
	v_lshlrev_b32_e32 v184, 2, v37
	v_xor_b32_e32 v37, 16, v3
	v_cmp_lt_i32_e32 vcc, v37, v36
	v_mov_b32_e32 v43, v1
	s_ashr_i32 s5, s4, 31
	v_cndmask_b32_e32 v37, v3, v37, vcc
	v_lshlrev_b32_e32 v185, 2, v37
	v_xor_b32_e32 v37, 32, v3
	v_cmp_lt_i32_e32 vcc, v37, v36
	v_or_b32_e32 v36, 0x100, v164
	v_lshlrev_b32_e32 v38, 2, v36
	v_lshl_add_u64 v[170:171], s[0:1], 0, v[38:39]
	v_or_b32_e32 v38, 0x200, v164
	v_lshlrev_b32_e32 v40, 2, v38
	v_lshl_add_u64 v[172:173], s[0:1], 0, v[40:41]
	v_or_b32_e32 v40, 0x300, v164
	v_lshlrev_b32_e32 v42, 2, v40
	v_lshl_add_u64 v[168:169], s[0:1], 0, v[0:1]
	v_lshl_add_u64 v[174:175], s[0:1], 0, v[42:43]
	s_lshl_b64 s[0:1], s[4:5], 5
	s_add_u32 s0, s28, s0
	s_addc_u32 s1, s29, s1
	s_add_u32 s6, s0, 0x1e500000
	s_addc_u32 s7, s1, 0
	s_lshl_b64 s[0:1], s[4:5], 11
	v_cndmask_b32_e32 v3, v3, v37, vcc
	s_add_u32 s0, s26, s0
	v_lshlrev_b32_e32 v186, 2, v3
	v_add_u32_e32 v187, 0, v0
	v_cmp_eq_u32_e32 vcc, 0, v2
	v_lshl_add_u64 v[166:167], s[54:55], 0, v[0:1]
	v_lshl_add_u64 v[176:177], s[56:57], 0, v[0:1]
	v_lshlrev_b32_e32 v0, 3, v2
	s_addc_u32 s1, s27, s1
	v_mov_b32_e32 v2, v1
	v_mov_b32_e32 v3, v1
	v_lshl_add_u64 v[178:179], s[0:1], 0, v[0:1]
	v_mov_b32_e32 v0, v1
	v_lshlrev_b32_e32 v188, 2, v36
	v_lshlrev_b32_e32 v189, 2, v38
	v_lshlrev_b32_e32 v190, 2, v40
	v_mov_b64_e32 v[66:67], v[2:3]
	v_mov_b64_e32 v[58:59], v[2:3]
	v_mov_b64_e32 v[50:51], v[2:3]
	v_mov_b64_e32 v[42:43], v[2:3]
	v_mov_b64_e32 v[62:63], v[2:3]
	v_mov_b64_e32 v[54:55], v[2:3]
	v_mov_b64_e32 v[46:47], v[2:3]
	v_mov_b64_e32 v[38:39], v[2:3]
	s_mov_b32 s10, -1
	v_mov_b32_e32 v191, 0x358637bd
	s_mov_b32 s5, 0x800000
	s_mov_b64 s[8:9], 0x800
	v_mov_b64_e32 v[64:65], v[0:1]
	v_mov_b64_e32 v[56:57], v[0:1]
	v_mov_b64_e32 v[48:49], v[0:1]
	v_mov_b64_e32 v[40:41], v[0:1]
	v_mov_b64_e32 v[60:61], v[0:1]
	v_mov_b64_e32 v[52:53], v[0:1]
	v_mov_b64_e32 v[44:45], v[0:1]
	v_mov_b64_e32 v[36:37], v[0:1]
	v_readfirstlane_b32 s100, v180
	v_lshlrev_b32_e32 v68, 2, v164
	s_lshr_b32 s100, s100, 6
	s_mul_i32 s100, s100, 12288
	s_add_i32 s100, s100, 0x8000
	s_add_i32 s101, s100, 12288
	s_mov_b32 s98, s100
	s_add_i32 s99, s100, 8192
	s_add_i32 s0, s4, 2
	s_cmp_ge_i32 s0, s33
	s_cbranch_scc1 .Lp1_pro_done
	s_add_i32 s11, s0, 0xffff8000
	s_ashr_i32 s1, s0, 31
	s_cmp_lt_i32 s0, 0x8000
	s_cselect_b32 s1, s1, 0
	s_cselect_b32 s0, s0, s11
	s_cselect_b32 s11, s37, s39
	s_cselect_b32 s12, s36, s38
	s_lshl_b64 s[0:1], s[0:1], 12
	s_add_u32 s0, s12, s0
	s_addc_u32 s1, s11, s1
	s_add_i32 m0, s100, 0
	s_nop 0
	global_load_lds_dwordx4 v68, s[0:1]
	global_load_lds_dwordx4 v68, s[0:1] offset:1024
	global_load_lds_dwordx4 v68, s[0:1] offset:2048
	global_load_lds_dwordx4 v68, s[0:1] offset:3072
	s_add_i32 s0, s4, 3
	s_cmp_ge_i32 s0, s33
	s_cbranch_scc1 .Lp1_pro_done
	s_add_i32 s11, s0, 0xffff8000
	s_ashr_i32 s1, s0, 31
	s_cmp_lt_i32 s0, 0x8000
	s_cselect_b32 s1, s1, 0
	s_cselect_b32 s0, s0, s11
	s_cselect_b32 s11, s37, s39
	s_cselect_b32 s12, s36, s38
	s_lshl_b64 s[0:1], s[0:1], 12
	s_add_u32 s0, s12, s0
	s_addc_u32 s1, s11, s1
	s_add_i32 m0, s100, 4096
	s_nop 0
	global_load_lds_dwordx4 v68, s[0:1]
	global_load_lds_dwordx4 v68, s[0:1] offset:1024
	global_load_lds_dwordx4 v68, s[0:1] offset:2048
	global_load_lds_dwordx4 v68, s[0:1] offset:3072

; __device__ __forceinline__ void phase1(const Args& a, LAS unsigned char* L) {
;     ...
;         f32x4 v[4]; float ss = 0.f;
; #pragma unroll
;         for (int j = 0; j < 4; ++j) { v[j] = nxv[j]; nxv[j] = nxw[j]; }
;         if (m + 2 < m_hi) { const int m1 = m + 2; const float* xr = (m1 < MP ? a.in[0] + (size_t)m1 * DM : a.in[1] + (size_t)(m1 - MP) * DM);
; #pragma unroll
;             for (int j = 0; j < 4; ++j) nxw[j] = *(const f32x4*)(xr + 4 * lane + 256 * j); }
.LBB0_116:
	s_or_b64 exec, exec, s[0:1]
	s_add_i32 s4, s4, 1
	s_add_u32 s6, s6, 32
	v_mov_b64_e32 v[22:23], v[6:7]
	v_mov_b64_e32 v[26:27], v[10:11]
	s_waitcnt lgkmcnt(2)
	v_mov_b64_e32 v[30:31], v[14:15]
	s_waitcnt lgkmcnt(0)
	v_mov_b64_e32 v[34:35], v[18:19]
	s_addc_u32 s7, s7, 0
	v_mov_b64_e32 v[20:21], v[4:5]
	v_mov_b64_e32 v[24:25], v[8:9]
	v_mov_b64_e32 v[28:29], v[12:13]
	v_mov_b64_e32 v[32:33], v[16:17]
	s_add_i32 s0, s4, 3
	s_cmp_lt_i32 s0, s33
	s_cbranch_scc1 .Lp1_pf
	s_waitcnt vmcnt(18)
	s_branch .Lp1_rd
.Lp1_pf:
	s_waitcnt vmcnt(26)
.Lp1_rd:
	v_lshl_add_u32 v68, v164, 2, s98
	ds_read_b128 v[16:19], v68
	ds_read_b128 v[12:15], v68 offset:1024
	ds_read_b128 v[8:11], v68 offset:2048
	ds_read_b128 v[4:7], v68 offset:3072
	s_mov_b32 s99, s98
	s_add_i32 s98, s98, 0x1000
	s_cmp_eq_u32 s98, s101
	s_cselect_b32 s98, s100, s98
	v_lshl_add_u64 v[178:179], v[178:179], 0, s[8:9]
	s_waitcnt lgkmcnt(0)
	s_cmp_lt_i32 s4, s33
	s_cbranch_scc0 .LBB0_123

; __device__ __forceinline__ void phase1(const Args& a, LAS unsigned char* L) {
;     ...
;         if (m + 2 < m_hi) { const int m1 = m + 2; const float* xr = (m1 < MP ? a.in[0] + (size_t)m1 * DM : a.in[1] + (size_t)(m1 - MP) * DM);
; #pragma unroll
;             for (int j = 0; j < 4; ++j) nxw[j] = *(const f32x4*)(xr + 4 * lane + 256 * j); }
.LBB0_119:
	s_add_i32 s0, s4, 4
	s_cmp_ge_i32 s0, s33
	s_cbranch_scc1 .LBB0_121
	s_add_i32 s11, s0, 0xffff8000
	s_ashr_i32 s1, s0, 31
	s_cmp_lt_i32 s0, 0x8000
	s_cselect_b32 s1, s1, 0
	s_cselect_b32 s0, s0, s11
	s_cselect_b32 s11, s37, s39
	s_cselect_b32 s12, s36, s38
	s_lshl_b64 s[0:1], s[0:1], 12
	s_add_u32 s0, s12, s0
	s_addc_u32 s1, s11, s1
	s_mov_b32 m0, s99
	s_nop 0
	global_load_lds_dwordx4 v0, s[0:1]
	global_load_lds_dwordx4 v0, s[0:1] offset:1024
	global_load_lds_dwordx4 v0, s[0:1] offset:2048
	global_load_lds_dwordx4 v0, s[0:1] offset:3072
